# attention: static s_setprio 1 for waves 4-7 (younger half), no per-segment toggling
# baseline (speedup 1.0000x reference)
; #define LAS __attribute__((address_space(3)))
; #define ATT_LOADK(kt_) do { _Pragma("unroll") for (int ks = 0; ks < 12; ++ks) kf[ks] = rowfrag32(Kt, KS, 32 * (kt_), 16 * ks, lane); } while (0)
; #define ATT_LOADV(kt_) do { _Pragma("unroll") for (int g = 0; g < 2; ++g) { const int rlo = 32 * (kt_) + 16 * g + 4 * hi; \
;             _Pragma("unroll") for (int dt = 0; dt < 4; ++dt) vf[4 * g + dt] = trfrag32(Vt, VS, rlo, rlo + 8, 32 * dt, lane); } } while (0)
; __device__ __forceinline__ void attn_unit(LAS unsigned char* lds, const Params& P, int b, int h, int qb) {
;     ...
;     for (int jt = 0; jt < ntiles; ++jt) {
;         if (jt + 1 < ntiles) ATT_LOAD(jt + 1);
;         const LAS unsigned char* Kt = lds + (jt & 1) * BUF; const LAS unsigned char* Vt = Kt + VOFF;
;         const bool do1 = 64 * jt + 32 <= qmin + 31;
;         if (64 * jt <= qmin + 31) {
;             ATT_LOADK(0);
;             __builtin_amdgcn_sched_barrier(0);
;             ATT_SUBTILE(0, ATT_LOADV(0));
.LBB0_108:
	v_readfirstlane_b32 vcc_lo, v202
	s_cmpk_lt_u32 vcc_lo, 0x100
	s_cbranch_scc1 .Lattn_sp_4
	s_setprio 1
